# prep phase split: each of the 192 modulation-GEMV workgroups also takes one transpose tile from the end of the range (the other 320 stride over the rest)
# baseline (speedup 1.0000x reference)
; DI void ph_prep(const Params& p, unsigned char* smem, int bid, int nb) {
;     ...
;   for (int it = bid; it < total; it += nb) {
;     if (it >= n_mod_items && it < n_mod_items + WT_TILES) {
;       wt_tile(p, 0, it - n_mod_items, smem, tid);
.LBB0_19:
	v_readlane_b32 s1, v253, 43
	s_cmpk_eq_i32 s1, 0x200
	s_cbranch_scc0 .Lpp_std
	v_readlane_b32 s10, v253, 42
	s_nop 0
	s_cmpk_lt_u32 s10, 0xc0
	s_cbranch_scc0 .Lpp_big
	s_cmpk_lt_i32 s0, 0xc0
	s_cbranch_scc0 .LBB0_61
	s_add_i32 s0, s10, 0x561
	s_branch .LBB0_20
.Lpp_big:
	s_addk_i32 s0, 0x140
	s_cmpk_lt_i32 s0, 0x561
	s_cbranch_scc0 .LBB0_61
	s_branch .LBB0_20
